# norm phases: hand-pipelined fast path for the 8 latent rows per wave (4 rows of loads in flight, counted vmcnt) on top of RET-chain pipelining
# speedup vs baseline: 1.0038x; 1.0037x over previous
; #define NP_LOAD(dst_, r_) do { const float* s_ = NP_SRC(r_); _Pragma("unroll") for (int j = 0; j < 4; ++j) dst_[j] = *(const f32x4*)(s_ + 4 * lane + 256 * j); } while (0)
; DI void norm_phase(const Ctx& a, int layer, int sub, bool first, const float* P, int nsl, int nrows) {
;     ...
;     for (int j = 0; j < 4; ++j) { gg[j] = *(const f32x4*)(g + 4 * lane + 256 * j); n1[j] = (f32x4){0.f, 0.f, 0.f, 0.f}; n2[j] = n1[j]; sc[j] = n1[j]; sh[j] = n1[j]; }
;     NP_LOAD(n1, rbeg);
;     if (rbeg + NGW < rend) NP_LOAD(n2, rbeg + NGW);
;     int mr_cur = -1;
;     for (int row = rbeg; row < rend; row += NGW) {
; #pragma unroll
;         for (int j = 0; j < 4; ++j) { v[j] = n1[j]; n1[j] = n2[j]; }
;         if (row + 2 * NGW < rend) NP_LOAD(n2, row + 2 * NGW);
;         const int mr = row < ML ? (row >> 12) : 4;
;         if (mr != mr_cur) { mr_cur = mr;
; #pragma unroll
;             for (int j = 0; j < 4; ++j) { sh[j] = *(const f32x4*)(modl + (size_t)mr * MODW + 4 * lane + 256 * j); sc[j] = *(const f32x4*)(modl + (size_t)mr * MODW + 1024 + 4 * lane + 256 * j) + 1.f; } }
;         const bool fold = !first && row >= ML;
;         float ss = 0.f;
;         if (fold) {
;             for (int sl0 = 0; sl0 < nsl; sl0 += 4) {
;                 f32x4 t[4][4]; float wq[4];
; #pragma unroll
;                 for (int u = 0; u < 4; ++u) { const int sl = sl0 + u < nsl ? sl0 + u : nsl - 1; wq[u] = sl0 + u < nsl ? 1.f : 0.f;
; #pragma unroll
;                     for (int j = 0; j < 4; ++j) t[u][j] = *(const f32x4*)(P + ((size_t)sl * MC + (row - ML)) * D + 4 * lane + 256 * j); }
; #pragma unroll
;                 for (int u = 0; u < 4; ++u)
; #pragma unroll
;                     for (int j = 0; j < 4; ++j) v[j] = v[j] + t[u][j] * wq[u];
;             }
;         }
; #pragma unroll
;         for (int j = 0; j < 4; ++j) ss += (v[j][0] * v[j][0] + v[j][1] * v[j][1]) + (v[j][2] * v[j][2] + v[j][3] * v[j][3]);
;         const float rstd = 1.f / sqrtf(wave_sum(ss, lane) * (1.f / 1024.f) + 1e-6f);
.LBB0_501:
	s_or_b64 exec, exec, s[42:43]
	v_readlane_b32 s6, v254, 59
	v_readlane_b32 s7, v254, 60
	s_and_b64 s[42:43], s[6:7], exec
	v_readlane_b32 s6, v254, 55
	v_readlane_b32 s7, v254, 56
	s_cselect_b32 s20, 1, 4
	s_and_b64 s[42:43], s[6:7], exec
	s_cselect_b32 s20, 8, s20
	s_and_b64 s[42:43], s[40:41], exec
	s_mov_b32 s1, 0x1103a200
	s_cselect_b32 s21, s1, 0x1983a200
	s_add_u32 s42, s38, s21
	s_addc_u32 s43, s39, 0
	s_and_b64 s[40:41], s[40:41], exec
	v_readlane_b32 s1, v255, 10
	s_cselect_b32 s48, s20, 11
	s_mul_hi_i32 s20, s75, 0x2d000
	s_add_u32 s21, s38, s1
	s_addc_u32 s20, s39, s20
	s_mulk_i32 s46, 0x3000
	v_mov_b32_e32 v62, v147
	v_mov_b32_e32 v63, v147
	s_add_u32 s38, s21, s46
	v_lshlrev_b32_e32 v44, 1, v46
	v_mov_b32_e32 v45, v147
	v_mov_b32_e32 v60, v147
	v_mov_b32_e32 v61, v147
	v_mov_b64_e32 v[70:71], v[62:63]
	v_mov_b64_e32 v[74:75], v[62:63]
	v_mov_b64_e32 v[78:79], v[62:63]
	v_mov_b64_e32 v[86:87], v[62:63]
	v_mov_b64_e32 v[82:83], v[62:63]
	v_mov_b64_e32 v[90:91], v[62:63]
	v_mov_b64_e32 v[94:95], v[62:63]
	s_addc_u32 s39, s20, 0
	s_add_i32 s49, s48, -1
	v_lshl_add_u64 v[98:99], s[42:43], 0, v[146:147]
	v_xor_b32_e32 v108, 64, v46
	v_xor_b32_e32 v109, 0x80, v46
	v_lshl_add_u64 v[100:101], s[4:5], 0, v[44:45]
	v_mov_b32_e32 v110, -1
	s_mov_b64 s[44:45], 0
	s_xor_b64 s[46:47], s[30:31], -1
	v_mov_b64_e32 v[68:69], v[60:61]
	v_mov_b64_e32 v[72:73], v[60:61]
	v_mov_b64_e32 v[76:77], v[60:61]
	v_mov_b64_e32 v[84:85], v[60:61]
	v_mov_b64_e32 v[80:81], v[60:61]
	v_mov_b64_e32 v[88:89], v[60:61]
	v_mov_b64_e32 v[92:93], v[60:61]
	s_and_b64 vcc, exec, s[46:47]
	s_cbranch_vccz .LBB0_503
	s_cmp_eq_u32 s25, 0x800
	s_cbranch_scc0 .LBB0_503
	s_add_u32 s20, s38, 0x0
	s_addc_u32 s21, s39, 0
	v_lshl_add_u64 v[94:95], s[20:21], 0, v[146:147]
	global_load_dwordx4 v[60:63], v[94:95], off
	global_load_dwordx4 v[64:67], v[94:95], off offset:1024
	global_load_dwordx4 v[68:71], v[94:95], off offset:2048
	global_load_dwordx4 v[72:75], v[94:95], off offset:3072
	s_add_u32 s20, s20, 0x1000
	s_addc_u32 s21, s21, 0
	v_lshl_add_u64 v[94:95], s[20:21], 0, v[146:147]
	global_load_dwordx4 v[76:79], v[94:95], off
	global_load_dwordx4 v[80:83], v[94:95], off offset:1024
	global_load_dwordx4 v[84:87], v[94:95], off offset:2048
	global_load_dwordx4 v[88:91], v[94:95], off offset:3072
	v_add_u32_e32 v58, 0x1000, v96
	v_mov_b32_e32 v59, v147
	v_lshlrev_b64 v[94:95], 12, v[58:59]
	v_lshl_add_u64 v[94:95], s[34:35], 0, v[94:95]
	v_lshl_add_u64 v[94:95], v[94:95], 0, v[146:147]
	global_load_dwordx4 v[112:115], v[94:95], off
	global_load_dwordx4 v[116:119], v[94:95], off offset:1024
	global_load_dwordx4 v[120:123], v[94:95], off offset:2048
	global_load_dwordx4 v[124:127], v[94:95], off offset:3072
	v_add_u32_e32 v58, 0x1800, v96
	v_mov_b32_e32 v59, v147
	v_lshlrev_b64 v[94:95], 12, v[58:59]
	v_lshl_add_u64 v[94:95], s[34:35], 0, v[94:95]
	v_lshl_add_u64 v[94:95], v[94:95], 0, v[146:147]
	global_load_dwordx4 v[128:131], v[94:95], off
	global_load_dwordx4 v[132:135], v[94:95], off offset:1024
	global_load_dwordx4 v[136:139], v[94:95], off offset:2048
	global_load_dwordx4 v[140:143], v[94:95], off offset:3072
	s_waitcnt vmcnt(8)
	v_pk_add_f32 v[76:77], v[76:77], 1.0 op_sel_hi:[1,0]
	v_pk_add_f32 v[78:79], v[78:79], 1.0 op_sel_hi:[1,0]
	v_pk_add_f32 v[80:81], v[80:81], 1.0 op_sel_hi:[1,0]
	v_pk_add_f32 v[82:83], v[82:83], 1.0 op_sel_hi:[1,0]
	v_pk_add_f32 v[84:85], v[84:85], 1.0 op_sel_hi:[1,0]
	v_pk_add_f32 v[86:87], v[86:87], 1.0 op_sel_hi:[1,0]
	v_pk_add_f32 v[88:89], v[88:89], 1.0 op_sel_hi:[1,0]
	v_pk_add_f32 v[90:91], v[90:91], 1.0 op_sel_hi:[1,0]
	v_pk_mul_f32 v[52:53], v[28:29], v[28:29]
	v_pk_mul_f32 v[54:55], v[30:31], v[30:31]
	v_pk_fma_f32 v[52:53], v[24:25], v[24:25], v[52:53]
	v_pk_fma_f32 v[54:55], v[26:27], v[26:27], v[54:55]
	v_pk_fma_f32 v[52:53], v[20:21], v[20:21], v[52:53]
	v_pk_fma_f32 v[54:55], v[22:23], v[22:23], v[54:55]
	v_pk_fma_f32 v[52:53], v[16:17], v[16:17], v[52:53]
	v_pk_fma_f32 v[54:55], v[18:19], v[18:19], v[54:55]
	v_pk_add_f32 v[52:53], v[52:53], v[54:55]
	s_add_u32 s20, s38, 0x9000
	s_addc_u32 s21, s39, 0
	v_lshl_add_u64 v[94:95], s[20:21], 0, v[146:147]
	global_load_dwordx4 v[158:161], v[94:95], off
	global_load_dwordx4 v[162:165], v[94:95], off offset:1024
	global_load_dwordx4 v[166:169], v[94:95], off offset:2048
	global_load_dwordx4 v[170:173], v[94:95], off offset:3072
	s_add_u32 s20, s20, 0x1000
	s_addc_u32 s21, s21, 0
	v_lshl_add_u64 v[94:95], s[20:21], 0, v[146:147]
	global_load_dwordx4 v[174:177], v[94:95], off
	global_load_dwordx4 v[178:181], v[94:95], off offset:1024
	global_load_dwordx4 v[182:185], v[94:95], off offset:2048
	global_load_dwordx4 v[186:189], v[94:95], off offset:3072
	v_add_f32_e32 v97, v52, v53
	s_nop 1
	v_add_f32_dpp v97, v97, v97 quad_perm:[1,0,3,2] row_mask:0xf bank_mask:0xf
	s_nop 1
	v_add_f32_dpp v97, v97, v97 quad_perm:[2,3,0,1] row_mask:0xf bank_mask:0xf
	s_nop 1
	v_add_f32_dpp v97, v97, v97 row_ror:4 row_mask:0xf bank_mask:0xf
	s_nop 1
	v_add_f32_dpp v97, v97, v97 row_ror:8 row_mask:0xf bank_mask:0xf
	ds_bpermute_b32 v103, v108, v97
	v_add_u32_e32 v58, 0x0, v96
	v_mov_b32_e32 v59, v147
	v_lshlrev_b64 v[92:93], 11, v[58:59]
	v_lshl_add_u64 v[92:93], v[100:101], 0, v[92:93]
	s_waitcnt lgkmcnt(0)
	v_add_f32_e32 v103, v97, v103
	ds_bpermute_b32 v106, v109, v103
	s_waitcnt lgkmcnt(0)
; DI unsigned pk2(float lo, float hi) { const f32x2 v = {lo, hi}; const hbf16x2 b = __builtin_convertvector(v, hbf16x2); return __builtin_bit_cast(unsigned, b); }
; DI void norm_phase(const Ctx& a, int layer, int sub, bool first, const float* P, int nsl, int nrows) {
;     ...
; #pragma unroll
;         for (int j = 0; j < 4; ++j) ss += (v[j][0] * v[j][0] + v[j][1] * v[j][1]) + (v[j][2] * v[j][2] + v[j][3] * v[j][3]);
;         const float rstd = 1.f / sqrtf(wave_sum(ss, lane) * (1.f / 1024.f) + 1e-6f);
; #pragma unroll
;         for (int j = 0; j < 4; ++j) {
;             const int c = 4 * lane + 256 * j;
;             if ((first && row >= ML) || fold) *(f32x4*)(H + (size_t)row * 1024 + c) = v[j];
;             f32x4 y = v[j] * rstd * gg[j]; y = y * sc[j] + sh[j];
;             u32x2 w; w.x = pk2(y[0], y[1]); w.y = pk2(y[2], y[3]);
;             *(u32x2*)(XN + (size_t)row * 1024 + c) = w;
;         }
	v_add_f32_e32 v97, v103, v106
	v_fmamk_f32 v97, v97, 0x3a800000, v203
	v_mul_f32_e32 v103, 0x4f800000, v97
	v_cmp_gt_f32_e32 vcc, s26, v97
	s_nop 1
	v_cndmask_b32_e32 v97, v97, v103, vcc
	v_sqrt_f32_e32 v103, v97
	s_nop 0
	v_add_u32_e32 v106, -1, v103
	v_fma_f32 v111, -v106, v103, v97
	v_add_u32_e32 v107, 1, v103
	v_cmp_ge_f32_e64 s[42:43], 0, v111
	s_nop 1
	v_cndmask_b32_e64 v106, v103, v106, s[42:43]
	v_fma_f32 v103, -v107, v103, v97
	v_cmp_lt_f32_e64 s[42:43], 0, v103
	s_nop 1
	v_cndmask_b32_e64 v103, v106, v107, s[42:43]
	v_mul_f32_e32 v106, 0x37800000, v103
	v_cndmask_b32_e32 v103, v103, v106, vcc
	v_cmp_class_f32_e32 vcc, v97, v201
	s_nop 1
	v_cndmask_b32_e32 v97, v103, v97, vcc
	v_div_scale_f32 v103, s[30:31], v97, v97, 1.0
	v_rcp_f32_e32 v106, v103
	s_nop 0
	v_fma_f32 v107, -v103, v106, 1.0
	v_fmac_f32_e32 v106, v107, v106
	v_div_scale_f32 v107, vcc, 1.0, v97, 1.0
	v_mul_f32_e32 v111, v107, v106
	v_fma_f32 v45, -v103, v111, v107
	v_fmac_f32_e32 v111, v45, v106
	v_fma_f32 v103, -v103, v111, v107
	v_div_fmas_f32 v103, v103, v106, v111
	v_div_fixup_f32 v106, v103, v97, 1.0
	v_mov_b32_e32 v107, v106
	v_pk_mul_f32 v[28:29], v[28:29], v[106:107]
	v_pk_mul_f32 v[30:31], v[30:31], v[106:107]
	v_pk_mul_f32 v[28:29], v[0:1], v[28:29]
	v_pk_mul_f32 v[30:31], v[2:3], v[30:31]
	v_pk_fma_f32 v[28:29], v[76:77], v[28:29], v[60:61]
	v_pk_fma_f32 v[30:31], v[78:79], v[30:31], v[62:63]
	v_cvt_pk_bf16_f32 v54, v28, v29
	v_cvt_pk_bf16_f32 v55, v30, v31
	global_store_dwordx2 v[92:93], v[54:55], off
	v_pk_mul_f32 v[24:25], v[24:25], v[106:107]
	v_pk_mul_f32 v[26:27], v[26:27], v[106:107]
	v_pk_mul_f32 v[24:25], v[4:5], v[24:25]
	v_pk_mul_f32 v[26:27], v[6:7], v[26:27]
	v_pk_fma_f32 v[24:25], v[80:81], v[24:25], v[64:65]
	v_pk_fma_f32 v[26:27], v[82:83], v[26:27], v[66:67]
	v_cvt_pk_bf16_f32 v56, v24, v25
	v_cvt_pk_bf16_f32 v57, v26, v27
	global_store_dwordx2 v[92:93], v[56:57], off offset:512
	v_pk_mul_f32 v[20:21], v[20:21], v[106:107]
	v_pk_mul_f32 v[22:23], v[22:23], v[106:107]
	v_pk_mul_f32 v[20:21], v[8:9], v[20:21]
	v_pk_mul_f32 v[22:23], v[10:11], v[22:23]
	v_pk_fma_f32 v[20:21], v[84:85], v[20:21], v[68:69]
	v_pk_fma_f32 v[22:23], v[86:87], v[22:23], v[70:71]
	v_cvt_pk_bf16_f32 v54, v20, v21
	v_cvt_pk_bf16_f32 v55, v22, v23
	global_store_dwordx2 v[92:93], v[54:55], off offset:1024
	v_pk_mul_f32 v[16:17], v[16:17], v[106:107]
	v_pk_mul_f32 v[18:19], v[18:19], v[106:107]
	v_pk_mul_f32 v[16:17], v[12:13], v[16:17]
	v_pk_mul_f32 v[18:19], v[14:15], v[18:19]
	v_pk_fma_f32 v[16:17], v[88:89], v[16:17], v[72:73]
	v_pk_fma_f32 v[18:19], v[90:91], v[18:19], v[74:75]
	v_cvt_pk_bf16_f32 v56, v16, v17
	v_cvt_pk_bf16_f32 v57, v18, v19
	global_store_dwordx2 v[92:93], v[56:57], off offset:1536
	v_add_u32_e32 v58, 0x2000, v96
	v_mov_b32_e32 v59, v147
	v_lshlrev_b64 v[94:95], 12, v[58:59]
	v_lshl_add_u64 v[94:95], s[34:35], 0, v[94:95]
	v_lshl_add_u64 v[94:95], v[94:95], 0, v[146:147]
	global_load_dwordx4 v[28:31], v[94:95], off
	global_load_dwordx4 v[24:27], v[94:95], off offset:1024
	global_load_dwordx4 v[20:23], v[94:95], off offset:2048
	global_load_dwordx4 v[16:19], v[94:95], off offset:3072
	v_pk_mul_f32 v[52:53], v[36:37], v[36:37]
	v_pk_mul_f32 v[54:55], v[38:39], v[38:39]
	v_pk_fma_f32 v[52:53], v[40:41], v[40:41], v[52:53]
	v_pk_fma_f32 v[54:55], v[42:43], v[42:43], v[54:55]
	v_pk_fma_f32 v[52:53], v[48:49], v[48:49], v[52:53]
	v_pk_fma_f32 v[54:55], v[50:51], v[50:51], v[54:55]
	v_pk_fma_f32 v[52:53], v[32:33], v[32:33], v[52:53]
	v_pk_fma_f32 v[54:55], v[34:35], v[34:35], v[54:55]
	v_pk_add_f32 v[52:53], v[52:53], v[54:55]
	v_add_f32_e32 v97, v52, v53
	s_nop 1
	v_add_f32_dpp v97, v97, v97 quad_perm:[1,0,3,2] row_mask:0xf bank_mask:0xf
	s_nop 1
	v_add_f32_dpp v97, v97, v97 quad_perm:[2,3,0,1] row_mask:0xf bank_mask:0xf
	s_nop 1
	v_add_f32_dpp v97, v97, v97 row_ror:4 row_mask:0xf bank_mask:0xf
	s_nop 1
	v_add_f32_dpp v97, v97, v97 row_ror:8 row_mask:0xf bank_mask:0xf
	ds_bpermute_b32 v103, v108, v97
	v_add_u32_e32 v58, 0x800, v96
	v_mov_b32_e32 v59, v147
	v_lshlrev_b64 v[92:93], 11, v[58:59]
	v_lshl_add_u64 v[92:93], v[100:101], 0, v[92:93]
	s_waitcnt lgkmcnt(0)
	v_add_f32_e32 v103, v97, v103
	ds_bpermute_b32 v106, v109, v103
	s_waitcnt lgkmcnt(0)
	v_add_f32_e32 v97, v103, v106
	v_fmamk_f32 v97, v97, 0x3a800000, v203
	v_mul_f32_e32 v103, 0x4f800000, v97
	v_cmp_gt_f32_e32 vcc, s26, v97
	s_nop 1
	v_cndmask_b32_e32 v97, v97, v103, vcc
	v_sqrt_f32_e32 v103, v97
	s_nop 0
	v_add_u32_e32 v106, -1, v103
	v_fma_f32 v111, -v106, v103, v97
	v_add_u32_e32 v107, 1, v103
	v_cmp_ge_f32_e64 s[42:43], 0, v111
	s_nop 1
	v_cndmask_b32_e64 v106, v103, v106, s[42:43]
	v_fma_f32 v103, -v107, v103, v97
	v_cmp_lt_f32_e64 s[42:43], 0, v103
	s_nop 1
	v_cndmask_b32_e64 v103, v106, v107, s[42:43]
	v_mul_f32_e32 v106, 0x37800000, v103
	v_cndmask_b32_e32 v103, v103, v106, vcc
	v_cmp_class_f32_e32 vcc, v97, v201
	s_nop 1
	v_cndmask_b32_e32 v97, v103, v97, vcc
	v_div_scale_f32 v103, s[30:31], v97, v97, 1.0
	v_rcp_f32_e32 v106, v103
	s_nop 0
	v_fma_f32 v107, -v103, v106, 1.0
	v_fmac_f32_e32 v106, v107, v106
	v_div_scale_f32 v107, vcc, 1.0, v97, 1.0
	v_mul_f32_e32 v111, v107, v106
	v_fma_f32 v45, -v103, v111, v107
	v_fmac_f32_e32 v111, v45, v106
	v_fma_f32 v103, -v103, v111, v107
	v_div_fmas_f32 v103, v103, v106, v111
	v_div_fixup_f32 v106, v103, v97, 1.0
	v_mov_b32_e32 v107, v106
	v_pk_mul_f32 v[36:37], v[36:37], v[106:107]
	v_pk_mul_f32 v[38:39], v[38:39], v[106:107]
	v_pk_mul_f32 v[36:37], v[0:1], v[36:37]
	v_pk_mul_f32 v[38:39], v[2:3], v[38:39]
	v_pk_fma_f32 v[36:37], v[76:77], v[36:37], v[60:61]
	v_pk_fma_f32 v[38:39], v[78:79], v[38:39], v[62:63]
	v_cvt_pk_bf16_f32 v54, v36, v37
; DI unsigned pk2(float lo, float hi) { const f32x2 v = {lo, hi}; const hbf16x2 b = __builtin_convertvector(v, hbf16x2); return __builtin_bit_cast(unsigned, b); }
; DI void norm_phase(const Ctx& a, int layer, int sub, bool first, const float* P, int nsl, int nrows) {
;     ...
;         const int mr = row < ML ? (row >> 12) : 4;
;         if (mr != mr_cur) { mr_cur = mr;
; #pragma unroll
;             for (int j = 0; j < 4; ++j) { sh[j] = *(const f32x4*)(modl + (size_t)mr * MODW + 4 * lane + 256 * j); sc[j] = *(const f32x4*)(modl + (size_t)mr * MODW + 1024 + 4 * lane + 256 * j) + 1.f; } }
;         const bool fold = !first && row >= ML;
;         float ss = 0.f;
;         if (fold) {
;             for (int sl0 = 0; sl0 < nsl; sl0 += 4) {
;                 f32x4 t[4][4]; float wq[4];
; #pragma unroll
;                 for (int u = 0; u < 4; ++u) { const int sl = sl0 + u < nsl ? sl0 + u : nsl - 1; wq[u] = sl0 + u < nsl ? 1.f : 0.f;
; #pragma unroll
;                     for (int j = 0; j < 4; ++j) t[u][j] = *(const f32x4*)(P + ((size_t)sl * MC + (row - ML)) * D + 4 * lane + 256 * j); }
; #pragma unroll
;                 for (int u = 0; u < 4; ++u)
; #pragma unroll
;                     for (int j = 0; j < 4; ++j) v[j] = v[j] + t[u][j] * wq[u];
;             }
;         }
; #pragma unroll
;         for (int j = 0; j < 4; ++j) ss += (v[j][0] * v[j][0] + v[j][1] * v[j][1]) + (v[j][2] * v[j][2] + v[j][3] * v[j][3]);
;         const float rstd = 1.f / sqrtf(wave_sum(ss, lane) * (1.f / 1024.f) + 1e-6f);
; #pragma unroll
;         for (int j = 0; j < 4; ++j) {
;             const int c = 4 * lane + 256 * j;
;             if ((first && row >= ML) || fold) *(f32x4*)(H + (size_t)row * 1024 + c) = v[j];
;             f32x4 y = v[j] * rstd * gg[j]; y = y * sc[j] + sh[j];
;             u32x2 w; w.x = pk2(y[0], y[1]); w.y = pk2(y[2], y[3]);
;             *(u32x2*)(XN + (size_t)row * 1024 + c) = w;
;         }
	v_cvt_pk_bf16_f32 v55, v38, v39
	global_store_dwordx2 v[92:93], v[54:55], off
	v_pk_mul_f32 v[40:41], v[40:41], v[106:107]
	v_pk_mul_f32 v[42:43], v[42:43], v[106:107]
	v_pk_mul_f32 v[40:41], v[4:5], v[40:41]
	v_pk_mul_f32 v[42:43], v[6:7], v[42:43]
	v_pk_fma_f32 v[40:41], v[80:81], v[40:41], v[64:65]
	v_pk_fma_f32 v[42:43], v[82:83], v[42:43], v[66:67]
	v_cvt_pk_bf16_f32 v56, v40, v41
	v_cvt_pk_bf16_f32 v57, v42, v43
	global_store_dwordx2 v[92:93], v[56:57], off offset:512
	v_pk_mul_f32 v[48:49], v[48:49], v[106:107]
	v_pk_mul_f32 v[50:51], v[50:51], v[106:107]
	v_pk_mul_f32 v[48:49], v[8:9], v[48:49]
	v_pk_mul_f32 v[50:51], v[10:11], v[50:51]
	v_pk_fma_f32 v[48:49], v[84:85], v[48:49], v[68:69]
	v_pk_fma_f32 v[50:51], v[86:87], v[50:51], v[70:71]
	v_cvt_pk_bf16_f32 v54, v48, v49
	v_cvt_pk_bf16_f32 v55, v50, v51
	global_store_dwordx2 v[92:93], v[54:55], off offset:1024
	v_pk_mul_f32 v[32:33], v[32:33], v[106:107]
	v_pk_mul_f32 v[34:35], v[34:35], v[106:107]
	v_pk_mul_f32 v[32:33], v[12:13], v[32:33]
	v_pk_mul_f32 v[34:35], v[14:15], v[34:35]
	v_pk_fma_f32 v[32:33], v[88:89], v[32:33], v[72:73]
	v_pk_fma_f32 v[34:35], v[90:91], v[34:35], v[74:75]
	v_cvt_pk_bf16_f32 v56, v32, v33
	v_cvt_pk_bf16_f32 v57, v34, v35
	global_store_dwordx2 v[92:93], v[56:57], off offset:1536
	v_add_u32_e32 v58, 0x2800, v96
	v_mov_b32_e32 v59, v147
	v_lshlrev_b64 v[94:95], 12, v[58:59]
	v_lshl_add_u64 v[94:95], s[34:35], 0, v[94:95]
	v_lshl_add_u64 v[94:95], v[94:95], 0, v[146:147]
	global_load_dwordx4 v[36:39], v[94:95], off
	global_load_dwordx4 v[40:43], v[94:95], off offset:1024
	global_load_dwordx4 v[48:51], v[94:95], off offset:2048
	global_load_dwordx4 v[32:35], v[94:95], off offset:3072
	s_waitcnt vmcnt(16)
	v_pk_add_f32 v[174:175], v[174:175], 1.0 op_sel_hi:[1,0]
	v_pk_add_f32 v[176:177], v[176:177], 1.0 op_sel_hi:[1,0]
	v_pk_add_f32 v[178:179], v[178:179], 1.0 op_sel_hi:[1,0]
	v_pk_add_f32 v[180:181], v[180:181], 1.0 op_sel_hi:[1,0]
	v_pk_add_f32 v[182:183], v[182:183], 1.0 op_sel_hi:[1,0]
	v_pk_add_f32 v[184:185], v[184:185], 1.0 op_sel_hi:[1,0]
	v_pk_add_f32 v[186:187], v[186:187], 1.0 op_sel_hi:[1,0]
	v_pk_add_f32 v[188:189], v[188:189], 1.0 op_sel_hi:[1,0]
	v_pk_mul_f32 v[52:53], v[112:113], v[112:113]
	v_pk_mul_f32 v[54:55], v[114:115], v[114:115]
	v_pk_fma_f32 v[52:53], v[116:117], v[116:117], v[52:53]
	v_pk_fma_f32 v[54:55], v[118:119], v[118:119], v[54:55]
	v_pk_fma_f32 v[52:53], v[120:121], v[120:121], v[52:53]
	v_pk_fma_f32 v[54:55], v[122:123], v[122:123], v[54:55]
	v_pk_fma_f32 v[52:53], v[124:125], v[124:125], v[52:53]
	v_pk_fma_f32 v[54:55], v[126:127], v[126:127], v[54:55]
	v_pk_add_f32 v[52:53], v[52:53], v[54:55]
	s_add_u32 s20, s38, 0x12000
	s_addc_u32 s21, s39, 0
	v_lshl_add_u64 v[94:95], s[20:21], 0, v[146:147]
	global_load_dwordx4 v[60:63], v[94:95], off
	global_load_dwordx4 v[64:67], v[94:95], off offset:1024
	global_load_dwordx4 v[68:71], v[94:95], off offset:2048
	global_load_dwordx4 v[72:75], v[94:95], off offset:3072
	s_add_u32 s20, s20, 0x1000
	s_addc_u32 s21, s21, 0
	v_lshl_add_u64 v[94:95], s[20:21], 0, v[146:147]
	global_load_dwordx4 v[76:79], v[94:95], off
	global_load_dwordx4 v[80:83], v[94:95], off offset:1024
	global_load_dwordx4 v[84:87], v[94:95], off offset:2048
	global_load_dwordx4 v[88:91], v[94:95], off offset:3072
	v_add_f32_e32 v97, v52, v53
	s_nop 1
	v_add_f32_dpp v97, v97, v97 quad_perm:[1,0,3,2] row_mask:0xf bank_mask:0xf
	s_nop 1
	v_add_f32_dpp v97, v97, v97 quad_perm:[2,3,0,1] row_mask:0xf bank_mask:0xf
	s_nop 1
	v_add_f32_dpp v97, v97, v97 row_ror:4 row_mask:0xf bank_mask:0xf
	s_nop 1
	v_add_f32_dpp v97, v97, v97 row_ror:8 row_mask:0xf bank_mask:0xf
	ds_bpermute_b32 v103, v108, v97
	v_add_u32_e32 v58, 0x1000, v96
	v_mov_b32_e32 v59, v147
	v_lshlrev_b64 v[92:93], 11, v[58:59]
	v_lshl_add_u64 v[92:93], v[100:101], 0, v[92:93]
	s_waitcnt lgkmcnt(0)
	v_add_f32_e32 v103, v97, v103
	ds_bpermute_b32 v106, v109, v103
	s_waitcnt lgkmcnt(0)
	v_add_f32_e32 v97, v103, v106
	v_fmamk_f32 v97, v97, 0x3a800000, v203
	v_mul_f32_e32 v103, 0x4f800000, v97
	v_cmp_gt_f32_e32 vcc, s26, v97
	s_nop 1
	v_cndmask_b32_e32 v97, v97, v103, vcc
	v_sqrt_f32_e32 v103, v97
	s_nop 0
	v_add_u32_e32 v106, -1, v103
	v_fma_f32 v111, -v106, v103, v97
	v_add_u32_e32 v107, 1, v103
	v_cmp_ge_f32_e64 s[42:43], 0, v111
	s_nop 1
	v_cndmask_b32_e64 v106, v103, v106, s[42:43]
	v_fma_f32 v103, -v107, v103, v97
	v_cmp_lt_f32_e64 s[42:43], 0, v103
	s_nop 1
	v_cndmask_b32_e64 v103, v106, v107, s[42:43]
	v_mul_f32_e32 v106, 0x37800000, v103
	v_cndmask_b32_e32 v103, v103, v106, vcc
	v_cmp_class_f32_e32 vcc, v97, v201
	s_nop 1
	v_cndmask_b32_e32 v97, v103, v97, vcc
	v_div_scale_f32 v103, s[30:31], v97, v97, 1.0
	v_rcp_f32_e32 v106, v103
	s_nop 0
	v_fma_f32 v107, -v103, v106, 1.0
	v_fmac_f32_e32 v106, v107, v106
	v_div_scale_f32 v107, vcc, 1.0, v97, 1.0
	v_mul_f32_e32 v111, v107, v106
	v_fma_f32 v45, -v103, v111, v107
	v_fmac_f32_e32 v111, v45, v106
	v_fma_f32 v103, -v103, v111, v107
	v_div_fmas_f32 v103, v103, v106, v111
	v_div_fixup_f32 v106, v103, v97, 1.0
	v_mov_b32_e32 v107, v106
	v_pk_mul_f32 v[112:113], v[112:113], v[106:107]
	v_pk_mul_f32 v[114:115], v[114:115], v[106:107]
	v_pk_mul_f32 v[112:113], v[0:1], v[112:113]
	v_pk_mul_f32 v[114:115], v[2:3], v[114:115]
	v_pk_fma_f32 v[112:113], v[174:175], v[112:113], v[158:159]
	v_pk_fma_f32 v[114:115], v[176:177], v[114:115], v[160:161]
	v_cvt_pk_bf16_f32 v54, v112, v113
	v_cvt_pk_bf16_f32 v55, v114, v115
	global_store_dwordx2 v[92:93], v[54:55], off
	v_pk_mul_f32 v[116:117], v[116:117], v[106:107]
	v_pk_mul_f32 v[118:119], v[118:119], v[106:107]
	v_pk_mul_f32 v[116:117], v[4:5], v[116:117]
; DI unsigned pk2(float lo, float hi) { const f32x2 v = {lo, hi}; const hbf16x2 b = __builtin_convertvector(v, hbf16x2); return __builtin_bit_cast(unsigned, b); }
; DI void norm_phase(const Ctx& a, int layer, int sub, bool first, const float* P, int nsl, int nrows) {
;     ...
; #pragma unroll
;         for (int j = 0; j < 4; ++j) ss += (v[j][0] * v[j][0] + v[j][1] * v[j][1]) + (v[j][2] * v[j][2] + v[j][3] * v[j][3]);
;         const float rstd = 1.f / sqrtf(wave_sum(ss, lane) * (1.f / 1024.f) + 1e-6f);
; #pragma unroll
;         for (int j = 0; j < 4; ++j) {
;             const int c = 4 * lane + 256 * j;
;             if ((first && row >= ML) || fold) *(f32x4*)(H + (size_t)row * 1024 + c) = v[j];
;             f32x4 y = v[j] * rstd * gg[j]; y = y * sc[j] + sh[j];
;             u32x2 w; w.x = pk2(y[0], y[1]); w.y = pk2(y[2], y[3]);
;             *(u32x2*)(XN + (size_t)row * 1024 + c) = w;
;         }
	v_pk_mul_f32 v[118:119], v[6:7], v[118:119]
	v_pk_fma_f32 v[116:117], v[178:179], v[116:117], v[162:163]
	v_pk_fma_f32 v[118:119], v[180:181], v[118:119], v[164:165]
	v_cvt_pk_bf16_f32 v56, v116, v117
	v_cvt_pk_bf16_f32 v57, v118, v119
	global_store_dwordx2 v[92:93], v[56:57], off offset:512
	v_pk_mul_f32 v[120:121], v[120:121], v[106:107]
	v_pk_mul_f32 v[122:123], v[122:123], v[106:107]
	v_pk_mul_f32 v[120:121], v[8:9], v[120:121]
	v_pk_mul_f32 v[122:123], v[10:11], v[122:123]
	v_pk_fma_f32 v[120:121], v[182:183], v[120:121], v[166:167]
	v_pk_fma_f32 v[122:123], v[184:185], v[122:123], v[168:169]
	v_cvt_pk_bf16_f32 v54, v120, v121
	v_cvt_pk_bf16_f32 v55, v122, v123
	global_store_dwordx2 v[92:93], v[54:55], off offset:1024
	v_pk_mul_f32 v[124:125], v[124:125], v[106:107]
	v_pk_mul_f32 v[126:127], v[126:127], v[106:107]
	v_pk_mul_f32 v[124:125], v[12:13], v[124:125]
	v_pk_mul_f32 v[126:127], v[14:15], v[126:127]
	v_pk_fma_f32 v[124:125], v[186:187], v[124:125], v[170:171]
	v_pk_fma_f32 v[126:127], v[188:189], v[126:127], v[172:173]
	v_cvt_pk_bf16_f32 v56, v124, v125
	v_cvt_pk_bf16_f32 v57, v126, v127
	global_store_dwordx2 v[92:93], v[56:57], off offset:1536
	v_add_u32_e32 v58, 0x3000, v96
	v_mov_b32_e32 v59, v147
	v_lshlrev_b64 v[94:95], 12, v[58:59]
	v_lshl_add_u64 v[94:95], s[34:35], 0, v[94:95]
	v_lshl_add_u64 v[94:95], v[94:95], 0, v[146:147]
	global_load_dwordx4 v[112:115], v[94:95], off
	global_load_dwordx4 v[116:119], v[94:95], off offset:1024
	global_load_dwordx4 v[120:123], v[94:95], off offset:2048
	global_load_dwordx4 v[124:127], v[94:95], off offset:3072
	v_pk_mul_f32 v[52:53], v[128:129], v[128:129]
	v_pk_mul_f32 v[54:55], v[130:131], v[130:131]
	v_pk_fma_f32 v[52:53], v[132:133], v[132:133], v[52:53]
	v_pk_fma_f32 v[54:55], v[134:135], v[134:135], v[54:55]
	v_pk_fma_f32 v[52:53], v[136:137], v[136:137], v[52:53]
	v_pk_fma_f32 v[54:55], v[138:139], v[138:139], v[54:55]
	v_pk_fma_f32 v[52:53], v[140:141], v[140:141], v[52:53]
	v_pk_fma_f32 v[54:55], v[142:143], v[142:143], v[54:55]
	v_pk_add_f32 v[52:53], v[52:53], v[54:55]
	v_add_f32_e32 v97, v52, v53
	s_nop 1
	v_add_f32_dpp v97, v97, v97 quad_perm:[1,0,3,2] row_mask:0xf bank_mask:0xf
	s_nop 1
	v_add_f32_dpp v97, v97, v97 quad_perm:[2,3,0,1] row_mask:0xf bank_mask:0xf
	s_nop 1
	v_add_f32_dpp v97, v97, v97 row_ror:4 row_mask:0xf bank_mask:0xf
	s_nop 1
	v_add_f32_dpp v97, v97, v97 row_ror:8 row_mask:0xf bank_mask:0xf
	ds_bpermute_b32 v103, v108, v97
	v_add_u32_e32 v58, 0x1800, v96
	v_mov_b32_e32 v59, v147
	v_lshlrev_b64 v[92:93], 11, v[58:59]
	v_lshl_add_u64 v[92:93], v[100:101], 0, v[92:93]
	s_waitcnt lgkmcnt(0)
	v_add_f32_e32 v103, v97, v103
	ds_bpermute_b32 v106, v109, v103
	s_waitcnt lgkmcnt(0)
	v_add_f32_e32 v97, v103, v106
	v_fmamk_f32 v97, v97, 0x3a800000, v203
	v_mul_f32_e32 v103, 0x4f800000, v97
	v_cmp_gt_f32_e32 vcc, s26, v97
	s_nop 1
	v_cndmask_b32_e32 v97, v97, v103, vcc
	v_sqrt_f32_e32 v103, v97
	s_nop 0
	v_add_u32_e32 v106, -1, v103
	v_fma_f32 v111, -v106, v103, v97
	v_add_u32_e32 v107, 1, v103
	v_cmp_ge_f32_e64 s[42:43], 0, v111
	s_nop 1
	v_cndmask_b32_e64 v106, v103, v106, s[42:43]
	v_fma_f32 v103, -v107, v103, v97
	v_cmp_lt_f32_e64 s[42:43], 0, v103
	s_nop 1
	v_cndmask_b32_e64 v103, v106, v107, s[42:43]
	v_mul_f32_e32 v106, 0x37800000, v103
	v_cndmask_b32_e32 v103, v103, v106, vcc
	v_cmp_class_f32_e32 vcc, v97, v201
	s_nop 1
	v_cndmask_b32_e32 v97, v103, v97, vcc
	v_div_scale_f32 v103, s[30:31], v97, v97, 1.0
	v_rcp_f32_e32 v106, v103
	s_nop 0
	v_fma_f32 v107, -v103, v106, 1.0
	v_fmac_f32_e32 v106, v107, v106
	v_div_scale_f32 v107, vcc, 1.0, v97, 1.0
	v_mul_f32_e32 v111, v107, v106
	v_fma_f32 v45, -v103, v111, v107
	v_fmac_f32_e32 v111, v45, v106
	v_fma_f32 v103, -v103, v111, v107
	v_div_fmas_f32 v103, v103, v106, v111
	v_div_fixup_f32 v106, v103, v97, 1.0
	v_mov_b32_e32 v107, v106
	v_pk_mul_f32 v[128:129], v[128:129], v[106:107]
	v_pk_mul_f32 v[130:131], v[130:131], v[106:107]
	v_pk_mul_f32 v[128:129], v[0:1], v[128:129]
	v_pk_mul_f32 v[130:131], v[2:3], v[130:131]
	v_pk_fma_f32 v[128:129], v[174:175], v[128:129], v[158:159]
	v_pk_fma_f32 v[130:131], v[176:177], v[130:131], v[160:161]
	v_cvt_pk_bf16_f32 v54, v128, v129
	v_cvt_pk_bf16_f32 v55, v130, v131
	global_store_dwordx2 v[92:93], v[54:55], off
	v_pk_mul_f32 v[132:133], v[132:133], v[106:107]
	v_pk_mul_f32 v[134:135], v[134:135], v[106:107]
	v_pk_mul_f32 v[132:133], v[4:5], v[132:133]
	v_pk_mul_f32 v[134:135], v[6:7], v[134:135]
	v_pk_fma_f32 v[132:133], v[178:179], v[132:133], v[162:163]
	v_pk_fma_f32 v[134:135], v[180:181], v[134:135], v[164:165]
	v_cvt_pk_bf16_f32 v56, v132, v133
	v_cvt_pk_bf16_f32 v57, v134, v135
	global_store_dwordx2 v[92:93], v[56:57], off offset:512
	v_pk_mul_f32 v[136:137], v[136:137], v[106:107]
	v_pk_mul_f32 v[138:139], v[138:139], v[106:107]
	v_pk_mul_f32 v[136:137], v[8:9], v[136:137]
	v_pk_mul_f32 v[138:139], v[10:11], v[138:139]
	v_pk_fma_f32 v[136:137], v[182:183], v[136:137], v[166:167]
	v_pk_fma_f32 v[138:139], v[184:185], v[138:139], v[168:169]
	v_cvt_pk_bf16_f32 v54, v136, v137
	v_cvt_pk_bf16_f32 v55, v138, v139
	global_store_dwordx2 v[92:93], v[54:55], off offset:1024
	v_pk_mul_f32 v[140:141], v[140:141], v[106:107]
	v_pk_mul_f32 v[142:143], v[142:143], v[106:107]
	v_pk_mul_f32 v[140:141], v[12:13], v[140:141]
	v_pk_mul_f32 v[142:143], v[14:15], v[142:143]
	v_pk_fma_f32 v[140:141], v[186:187], v[140:141], v[170:171]
	v_pk_fma_f32 v[142:143], v[188:189], v[142:143], v[172:173]
	v_cvt_pk_bf16_f32 v56, v140, v141
	v_cvt_pk_bf16_f32 v57, v142, v143
	global_store_dwordx2 v[92:93], v[56:57], off offset:1536
	v_add_u32_e32 v58, 0x3800, v96
	v_mov_b32_e32 v59, v147
	v_lshlrev_b64 v[94:95], 12, v[58:59]
	v_lshl_add_u64 v[94:95], s[34:35], 0, v[94:95]
	v_lshl_add_u64 v[94:95], v[94:95], 0, v[146:147]
	global_load_dwordx4 v[128:131], v[94:95], off
	global_load_dwordx4 v[132:135], v[94:95], off offset:1024
	global_load_dwordx4 v[136:139], v[94:95], off offset:2048
	global_load_dwordx4 v[140:143], v[94:95], off offset:3072
	s_waitcnt vmcnt(16)
; DI unsigned pk2(float lo, float hi) { const f32x2 v = {lo, hi}; const hbf16x2 b = __builtin_convertvector(v, hbf16x2); return __builtin_bit_cast(unsigned, b); }
; DI void norm_phase(const Ctx& a, int layer, int sub, bool first, const float* P, int nsl, int nrows) {
;     ...
;         const int mr = row < ML ? (row >> 12) : 4;
;         if (mr != mr_cur) { mr_cur = mr;
; #pragma unroll
;             for (int j = 0; j < 4; ++j) { sh[j] = *(const f32x4*)(modl + (size_t)mr * MODW + 4 * lane + 256 * j); sc[j] = *(const f32x4*)(modl + (size_t)mr * MODW + 1024 + 4 * lane + 256 * j) + 1.f; } }
;         const bool fold = !first && row >= ML;
;         float ss = 0.f;
;         if (fold) {
;             for (int sl0 = 0; sl0 < nsl; sl0 += 4) {
;                 f32x4 t[4][4]; float wq[4];
; #pragma unroll
;                 for (int u = 0; u < 4; ++u) { const int sl = sl0 + u < nsl ? sl0 + u : nsl - 1; wq[u] = sl0 + u < nsl ? 1.f : 0.f;
; #pragma unroll
;                     for (int j = 0; j < 4; ++j) t[u][j] = *(const f32x4*)(P + ((size_t)sl * MC + (row - ML)) * D + 4 * lane + 256 * j); }
; #pragma unroll
;                 for (int u = 0; u < 4; ++u)
; #pragma unroll
;                     for (int j = 0; j < 4; ++j) v[j] = v[j] + t[u][j] * wq[u];
;             }
;         }
; #pragma unroll
;         for (int j = 0; j < 4; ++j) ss += (v[j][0] * v[j][0] + v[j][1] * v[j][1]) + (v[j][2] * v[j][2] + v[j][3] * v[j][3]);
;         const float rstd = 1.f / sqrtf(wave_sum(ss, lane) * (1.f / 1024.f) + 1e-6f);
; #pragma unroll
;         for (int j = 0; j < 4; ++j) {
;             const int c = 4 * lane + 256 * j;
;             if ((first && row >= ML) || fold) *(f32x4*)(H + (size_t)row * 1024 + c) = v[j];
;             f32x4 y = v[j] * rstd * gg[j]; y = y * sc[j] + sh[j];
;             u32x2 w; w.x = pk2(y[0], y[1]); w.y = pk2(y[2], y[3]);
;             *(u32x2*)(XN + (size_t)row * 1024 + c) = w;
;         }
	v_pk_add_f32 v[76:77], v[76:77], 1.0 op_sel_hi:[1,0]
	v_pk_add_f32 v[78:79], v[78:79], 1.0 op_sel_hi:[1,0]
	v_pk_add_f32 v[80:81], v[80:81], 1.0 op_sel_hi:[1,0]
	v_pk_add_f32 v[82:83], v[82:83], 1.0 op_sel_hi:[1,0]
	v_pk_add_f32 v[84:85], v[84:85], 1.0 op_sel_hi:[1,0]
	v_pk_add_f32 v[86:87], v[86:87], 1.0 op_sel_hi:[1,0]
	v_pk_add_f32 v[88:89], v[88:89], 1.0 op_sel_hi:[1,0]
	v_pk_add_f32 v[90:91], v[90:91], 1.0 op_sel_hi:[1,0]
	v_pk_mul_f32 v[52:53], v[28:29], v[28:29]
	v_pk_mul_f32 v[54:55], v[30:31], v[30:31]
	v_pk_fma_f32 v[52:53], v[24:25], v[24:25], v[52:53]
	v_pk_fma_f32 v[54:55], v[26:27], v[26:27], v[54:55]
	v_pk_fma_f32 v[52:53], v[20:21], v[20:21], v[52:53]
	v_pk_fma_f32 v[54:55], v[22:23], v[22:23], v[54:55]
	v_pk_fma_f32 v[52:53], v[16:17], v[16:17], v[52:53]
	v_pk_fma_f32 v[54:55], v[18:19], v[18:19], v[54:55]
	v_pk_add_f32 v[52:53], v[52:53], v[54:55]
	s_add_u32 s20, s38, 0x1b000
	s_addc_u32 s21, s39, 0
	v_lshl_add_u64 v[94:95], s[20:21], 0, v[146:147]
	global_load_dwordx4 v[158:161], v[94:95], off
	global_load_dwordx4 v[162:165], v[94:95], off offset:1024
	global_load_dwordx4 v[166:169], v[94:95], off offset:2048
	global_load_dwordx4 v[170:173], v[94:95], off offset:3072
	s_add_u32 s20, s20, 0x1000
	s_addc_u32 s21, s21, 0
	v_lshl_add_u64 v[94:95], s[20:21], 0, v[146:147]
	global_load_dwordx4 v[174:177], v[94:95], off
	global_load_dwordx4 v[178:181], v[94:95], off offset:1024
	global_load_dwordx4 v[182:185], v[94:95], off offset:2048
	global_load_dwordx4 v[186:189], v[94:95], off offset:3072
	v_add_f32_e32 v97, v52, v53
	s_nop 1
	v_add_f32_dpp v97, v97, v97 quad_perm:[1,0,3,2] row_mask:0xf bank_mask:0xf
	s_nop 1
	v_add_f32_dpp v97, v97, v97 quad_perm:[2,3,0,1] row_mask:0xf bank_mask:0xf
	s_nop 1
	v_add_f32_dpp v97, v97, v97 row_ror:4 row_mask:0xf bank_mask:0xf
	s_nop 1
	v_add_f32_dpp v97, v97, v97 row_ror:8 row_mask:0xf bank_mask:0xf
	ds_bpermute_b32 v103, v108, v97
	v_add_u32_e32 v58, 0x2000, v96
	v_mov_b32_e32 v59, v147
	v_lshlrev_b64 v[92:93], 11, v[58:59]
	v_lshl_add_u64 v[92:93], v[100:101], 0, v[92:93]
	s_waitcnt lgkmcnt(0)
	v_add_f32_e32 v103, v97, v103
	ds_bpermute_b32 v106, v109, v103
	s_waitcnt lgkmcnt(0)
	v_add_f32_e32 v97, v103, v106
	v_fmamk_f32 v97, v97, 0x3a800000, v203
	v_mul_f32_e32 v103, 0x4f800000, v97
	v_cmp_gt_f32_e32 vcc, s26, v97
	s_nop 1
	v_cndmask_b32_e32 v97, v97, v103, vcc
	v_sqrt_f32_e32 v103, v97
	s_nop 0
	v_add_u32_e32 v106, -1, v103
	v_fma_f32 v111, -v106, v103, v97
	v_add_u32_e32 v107, 1, v103
	v_cmp_ge_f32_e64 s[42:43], 0, v111
	s_nop 1
	v_cndmask_b32_e64 v106, v103, v106, s[42:43]
	v_fma_f32 v103, -v107, v103, v97
	v_cmp_lt_f32_e64 s[42:43], 0, v103
	s_nop 1
	v_cndmask_b32_e64 v103, v106, v107, s[42:43]
	v_mul_f32_e32 v106, 0x37800000, v103
	v_cndmask_b32_e32 v103, v103, v106, vcc
	v_cmp_class_f32_e32 vcc, v97, v201
	s_nop 1
	v_cndmask_b32_e32 v97, v103, v97, vcc
	v_div_scale_f32 v103, s[30:31], v97, v97, 1.0
	v_rcp_f32_e32 v106, v103
	s_nop 0
	v_fma_f32 v107, -v103, v106, 1.0
	v_fmac_f32_e32 v106, v107, v106
	v_div_scale_f32 v107, vcc, 1.0, v97, 1.0
	v_mul_f32_e32 v111, v107, v106
	v_fma_f32 v45, -v103, v111, v107
	v_fmac_f32_e32 v111, v45, v106
	v_fma_f32 v103, -v103, v111, v107
	v_div_fmas_f32 v103, v103, v106, v111
	v_div_fixup_f32 v106, v103, v97, 1.0
	v_mov_b32_e32 v107, v106
	v_pk_mul_f32 v[28:29], v[28:29], v[106:107]
	v_pk_mul_f32 v[30:31], v[30:31], v[106:107]
	v_pk_mul_f32 v[28:29], v[0:1], v[28:29]
	v_pk_mul_f32 v[30:31], v[2:3], v[30:31]
	v_pk_fma_f32 v[28:29], v[76:77], v[28:29], v[60:61]
	v_pk_fma_f32 v[30:31], v[78:79], v[30:31], v[62:63]
	v_cvt_pk_bf16_f32 v54, v28, v29
	v_cvt_pk_bf16_f32 v55, v30, v31
	global_store_dwordx2 v[92:93], v[54:55], off
	v_pk_mul_f32 v[24:25], v[24:25], v[106:107]
	v_pk_mul_f32 v[26:27], v[26:27], v[106:107]
	v_pk_mul_f32 v[24:25], v[4:5], v[24:25]
	v_pk_mul_f32 v[26:27], v[6:7], v[26:27]
	v_pk_fma_f32 v[24:25], v[80:81], v[24:25], v[64:65]
	v_pk_fma_f32 v[26:27], v[82:83], v[26:27], v[66:67]
	v_cvt_pk_bf16_f32 v56, v24, v25
	v_cvt_pk_bf16_f32 v57, v26, v27
	global_store_dwordx2 v[92:93], v[56:57], off offset:512
	v_pk_mul_f32 v[20:21], v[20:21], v[106:107]
	v_pk_mul_f32 v[22:23], v[22:23], v[106:107]
	v_pk_mul_f32 v[20:21], v[8:9], v[20:21]
	v_pk_mul_f32 v[22:23], v[10:11], v[22:23]
	v_pk_fma_f32 v[20:21], v[84:85], v[20:21], v[68:69]
	v_pk_fma_f32 v[22:23], v[86:87], v[22:23], v[70:71]
	v_cvt_pk_bf16_f32 v54, v20, v21
	v_cvt_pk_bf16_f32 v55, v22, v23
	global_store_dwordx2 v[92:93], v[54:55], off offset:1024
	v_pk_mul_f32 v[16:17], v[16:17], v[106:107]
	v_pk_mul_f32 v[18:19], v[18:19], v[106:107]
	v_pk_mul_f32 v[16:17], v[12:13], v[16:17]
	v_pk_mul_f32 v[18:19], v[14:15], v[18:19]
	v_pk_fma_f32 v[16:17], v[88:89], v[16:17], v[72:73]
	v_pk_fma_f32 v[18:19], v[90:91], v[18:19], v[74:75]
	v_cvt_pk_bf16_f32 v56, v16, v17
	v_cvt_pk_bf16_f32 v57, v18, v19
	global_store_dwordx2 v[92:93], v[56:57], off offset:1536
	v_pk_mul_f32 v[52:53], v[36:37], v[36:37]
	v_pk_mul_f32 v[54:55], v[38:39], v[38:39]
	v_pk_fma_f32 v[52:53], v[40:41], v[40:41], v[52:53]
	v_pk_fma_f32 v[54:55], v[42:43], v[42:43], v[54:55]
	v_pk_fma_f32 v[52:53], v[48:49], v[48:49], v[52:53]
	v_pk_fma_f32 v[54:55], v[50:51], v[50:51], v[54:55]
	v_pk_fma_f32 v[52:53], v[32:33], v[32:33], v[52:53]
	v_pk_fma_f32 v[54:55], v[34:35], v[34:35], v[54:55]
	v_pk_add_f32 v[52:53], v[52:53], v[54:55]
	v_add_f32_e32 v97, v52, v53
	s_nop 1
	v_add_f32_dpp v97, v97, v97 quad_perm:[1,0,3,2] row_mask:0xf bank_mask:0xf
	s_nop 1
	v_add_f32_dpp v97, v97, v97 quad_perm:[2,3,0,1] row_mask:0xf bank_mask:0xf
	s_nop 1
	v_add_f32_dpp v97, v97, v97 row_ror:4 row_mask:0xf bank_mask:0xf
	s_nop 1
	v_add_f32_dpp v97, v97, v97 row_ror:8 row_mask:0xf bank_mask:0xf
	ds_bpermute_b32 v103, v108, v97
	v_add_u32_e32 v58, 0x2800, v96
	v_mov_b32_e32 v59, v147
	v_lshlrev_b64 v[92:93], 11, v[58:59]
	v_lshl_add_u64 v[92:93], v[100:101], 0, v[92:93]
	s_waitcnt lgkmcnt(0)
; DI unsigned pk2(float lo, float hi) { const f32x2 v = {lo, hi}; const hbf16x2 b = __builtin_convertvector(v, hbf16x2); return __builtin_bit_cast(unsigned, b); }
; DI void norm_phase(const Ctx& a, int layer, int sub, bool first, const float* P, int nsl, int nrows) {
;     ...
; #pragma unroll
;         for (int j = 0; j < 4; ++j) ss += (v[j][0] * v[j][0] + v[j][1] * v[j][1]) + (v[j][2] * v[j][2] + v[j][3] * v[j][3]);
;         const float rstd = 1.f / sqrtf(wave_sum(ss, lane) * (1.f / 1024.f) + 1e-6f);
; #pragma unroll
;         for (int j = 0; j < 4; ++j) {
;             const int c = 4 * lane + 256 * j;
;             if ((first && row >= ML) || fold) *(f32x4*)(H + (size_t)row * 1024 + c) = v[j];
;             f32x4 y = v[j] * rstd * gg[j]; y = y * sc[j] + sh[j];
;             u32x2 w; w.x = pk2(y[0], y[1]); w.y = pk2(y[2], y[3]);
;             *(u32x2*)(XN + (size_t)row * 1024 + c) = w;
;         }
	v_add_f32_e32 v103, v97, v103
	ds_bpermute_b32 v106, v109, v103
	s_waitcnt lgkmcnt(0)
	v_add_f32_e32 v97, v103, v106
	v_fmamk_f32 v97, v97, 0x3a800000, v203
	v_mul_f32_e32 v103, 0x4f800000, v97
	v_cmp_gt_f32_e32 vcc, s26, v97
	s_nop 1
	v_cndmask_b32_e32 v97, v97, v103, vcc
	v_sqrt_f32_e32 v103, v97
	s_nop 0
	v_add_u32_e32 v106, -1, v103
	v_fma_f32 v111, -v106, v103, v97
	v_add_u32_e32 v107, 1, v103
	v_cmp_ge_f32_e64 s[42:43], 0, v111
	s_nop 1
	v_cndmask_b32_e64 v106, v103, v106, s[42:43]
	v_fma_f32 v103, -v107, v103, v97
	v_cmp_lt_f32_e64 s[42:43], 0, v103
	s_nop 1
	v_cndmask_b32_e64 v103, v106, v107, s[42:43]
	v_mul_f32_e32 v106, 0x37800000, v103
	v_cndmask_b32_e32 v103, v103, v106, vcc
	v_cmp_class_f32_e32 vcc, v97, v201
	s_nop 1
	v_cndmask_b32_e32 v97, v103, v97, vcc
	v_div_scale_f32 v103, s[30:31], v97, v97, 1.0
	v_rcp_f32_e32 v106, v103
	s_nop 0
	v_fma_f32 v107, -v103, v106, 1.0
	v_fmac_f32_e32 v106, v107, v106
	v_div_scale_f32 v107, vcc, 1.0, v97, 1.0
	v_mul_f32_e32 v111, v107, v106
	v_fma_f32 v45, -v103, v111, v107
	v_fmac_f32_e32 v111, v45, v106
	v_fma_f32 v103, -v103, v111, v107
	v_div_fmas_f32 v103, v103, v106, v111
	v_div_fixup_f32 v106, v103, v97, 1.0
	v_mov_b32_e32 v107, v106
	v_pk_mul_f32 v[36:37], v[36:37], v[106:107]
	v_pk_mul_f32 v[38:39], v[38:39], v[106:107]
	v_pk_mul_f32 v[36:37], v[0:1], v[36:37]
	v_pk_mul_f32 v[38:39], v[2:3], v[38:39]
	v_pk_fma_f32 v[36:37], v[76:77], v[36:37], v[60:61]
	v_pk_fma_f32 v[38:39], v[78:79], v[38:39], v[62:63]
	v_cvt_pk_bf16_f32 v54, v36, v37
	v_cvt_pk_bf16_f32 v55, v38, v39
	global_store_dwordx2 v[92:93], v[54:55], off
	v_pk_mul_f32 v[40:41], v[40:41], v[106:107]
	v_pk_mul_f32 v[42:43], v[42:43], v[106:107]
	v_pk_mul_f32 v[40:41], v[4:5], v[40:41]
	v_pk_mul_f32 v[42:43], v[6:7], v[42:43]
	v_pk_fma_f32 v[40:41], v[80:81], v[40:41], v[64:65]
	v_pk_fma_f32 v[42:43], v[82:83], v[42:43], v[66:67]
	v_cvt_pk_bf16_f32 v56, v40, v41
	v_cvt_pk_bf16_f32 v57, v42, v43
	global_store_dwordx2 v[92:93], v[56:57], off offset:512
	v_pk_mul_f32 v[48:49], v[48:49], v[106:107]
	v_pk_mul_f32 v[50:51], v[50:51], v[106:107]
	v_pk_mul_f32 v[48:49], v[8:9], v[48:49]
	v_pk_mul_f32 v[50:51], v[10:11], v[50:51]
	v_pk_fma_f32 v[48:49], v[84:85], v[48:49], v[68:69]
	v_pk_fma_f32 v[50:51], v[86:87], v[50:51], v[70:71]
	v_cvt_pk_bf16_f32 v54, v48, v49
	v_cvt_pk_bf16_f32 v55, v50, v51
	global_store_dwordx2 v[92:93], v[54:55], off offset:1024
	v_pk_mul_f32 v[32:33], v[32:33], v[106:107]
	v_pk_mul_f32 v[34:35], v[34:35], v[106:107]
	v_pk_mul_f32 v[32:33], v[12:13], v[32:33]
	v_pk_mul_f32 v[34:35], v[14:15], v[34:35]
	v_pk_fma_f32 v[32:33], v[88:89], v[32:33], v[72:73]
	v_pk_fma_f32 v[34:35], v[90:91], v[34:35], v[74:75]
	v_cvt_pk_bf16_f32 v56, v32, v33
	v_cvt_pk_bf16_f32 v57, v34, v35
	global_store_dwordx2 v[92:93], v[56:57], off offset:1536
	s_waitcnt vmcnt(8)
	v_pk_add_f32 v[174:175], v[174:175], 1.0 op_sel_hi:[1,0]
	v_pk_add_f32 v[176:177], v[176:177], 1.0 op_sel_hi:[1,0]
	v_pk_add_f32 v[178:179], v[178:179], 1.0 op_sel_hi:[1,0]
	v_pk_add_f32 v[180:181], v[180:181], 1.0 op_sel_hi:[1,0]
	v_pk_add_f32 v[182:183], v[182:183], 1.0 op_sel_hi:[1,0]
	v_pk_add_f32 v[184:185], v[184:185], 1.0 op_sel_hi:[1,0]
	v_pk_add_f32 v[186:187], v[186:187], 1.0 op_sel_hi:[1,0]
	v_pk_add_f32 v[188:189], v[188:189], 1.0 op_sel_hi:[1,0]
	v_pk_mul_f32 v[52:53], v[112:113], v[112:113]
	v_pk_mul_f32 v[54:55], v[114:115], v[114:115]
	v_pk_fma_f32 v[52:53], v[116:117], v[116:117], v[52:53]
	v_pk_fma_f32 v[54:55], v[118:119], v[118:119], v[54:55]
	v_pk_fma_f32 v[52:53], v[120:121], v[120:121], v[52:53]
	v_pk_fma_f32 v[54:55], v[122:123], v[122:123], v[54:55]
	v_pk_fma_f32 v[52:53], v[124:125], v[124:125], v[52:53]
	v_pk_fma_f32 v[54:55], v[126:127], v[126:127], v[54:55]
	v_pk_add_f32 v[52:53], v[52:53], v[54:55]
	v_add_f32_e32 v97, v52, v53
	s_nop 1
	v_add_f32_dpp v97, v97, v97 quad_perm:[1,0,3,2] row_mask:0xf bank_mask:0xf
	s_nop 1
	v_add_f32_dpp v97, v97, v97 quad_perm:[2,3,0,1] row_mask:0xf bank_mask:0xf
	s_nop 1
	v_add_f32_dpp v97, v97, v97 row_ror:4 row_mask:0xf bank_mask:0xf
	s_nop 1
	v_add_f32_dpp v97, v97, v97 row_ror:8 row_mask:0xf bank_mask:0xf
	ds_bpermute_b32 v103, v108, v97
	v_add_u32_e32 v58, 0x3000, v96
	v_mov_b32_e32 v59, v147
	v_lshlrev_b64 v[92:93], 11, v[58:59]
	v_lshl_add_u64 v[92:93], v[100:101], 0, v[92:93]
	s_waitcnt lgkmcnt(0)
	v_add_f32_e32 v103, v97, v103
	ds_bpermute_b32 v106, v109, v103
	s_waitcnt lgkmcnt(0)
; DI unsigned pk2(float lo, float hi) { const f32x2 v = {lo, hi}; const hbf16x2 b = __builtin_convertvector(v, hbf16x2); return __builtin_bit_cast(unsigned, b); }
; DI void norm_phase(const Ctx& a, int layer, int sub, bool first, const float* P, int nsl, int nrows) {
;     ...
; #pragma unroll
;         for (int j = 0; j < 4; ++j) ss += (v[j][0] * v[j][0] + v[j][1] * v[j][1]) + (v[j][2] * v[j][2] + v[j][3] * v[j][3]);
;         const float rstd = 1.f / sqrtf(wave_sum(ss, lane) * (1.f / 1024.f) + 1e-6f);
; #pragma unroll
;         for (int j = 0; j < 4; ++j) {
;             const int c = 4 * lane + 256 * j;
;             if ((first && row >= ML) || fold) *(f32x4*)(H + (size_t)row * 1024 + c) = v[j];
;             f32x4 y = v[j] * rstd * gg[j]; y = y * sc[j] + sh[j];
;             u32x2 w; w.x = pk2(y[0], y[1]); w.y = pk2(y[2], y[3]);
;             *(u32x2*)(XN + (size_t)row * 1024 + c) = w;
;         }
;     }
	v_add_f32_e32 v97, v103, v106
	v_fmamk_f32 v97, v97, 0x3a800000, v203
	v_mul_f32_e32 v103, 0x4f800000, v97
	v_cmp_gt_f32_e32 vcc, s26, v97
	s_nop 1
	v_cndmask_b32_e32 v97, v97, v103, vcc
	v_sqrt_f32_e32 v103, v97
	s_nop 0
	v_add_u32_e32 v106, -1, v103
	v_fma_f32 v111, -v106, v103, v97
	v_add_u32_e32 v107, 1, v103
	v_cmp_ge_f32_e64 s[42:43], 0, v111
	s_nop 1
	v_cndmask_b32_e64 v106, v103, v106, s[42:43]
	v_fma_f32 v103, -v107, v103, v97
	v_cmp_lt_f32_e64 s[42:43], 0, v103
	s_nop 1
	v_cndmask_b32_e64 v103, v106, v107, s[42:43]
	v_mul_f32_e32 v106, 0x37800000, v103
	v_cndmask_b32_e32 v103, v103, v106, vcc
	v_cmp_class_f32_e32 vcc, v97, v201
	s_nop 1
	v_cndmask_b32_e32 v97, v103, v97, vcc
	v_div_scale_f32 v103, s[30:31], v97, v97, 1.0
	v_rcp_f32_e32 v106, v103
	s_nop 0
	v_fma_f32 v107, -v103, v106, 1.0
	v_fmac_f32_e32 v106, v107, v106
	v_div_scale_f32 v107, vcc, 1.0, v97, 1.0
	v_mul_f32_e32 v111, v107, v106
	v_fma_f32 v45, -v103, v111, v107
	v_fmac_f32_e32 v111, v45, v106
	v_fma_f32 v103, -v103, v111, v107
	v_div_fmas_f32 v103, v103, v106, v111
	v_div_fixup_f32 v106, v103, v97, 1.0
	v_mov_b32_e32 v107, v106
	v_pk_mul_f32 v[112:113], v[112:113], v[106:107]
	v_pk_mul_f32 v[114:115], v[114:115], v[106:107]
	v_pk_mul_f32 v[112:113], v[0:1], v[112:113]
	v_pk_mul_f32 v[114:115], v[2:3], v[114:115]
	v_pk_fma_f32 v[112:113], v[174:175], v[112:113], v[158:159]
	v_pk_fma_f32 v[114:115], v[176:177], v[114:115], v[160:161]
	v_cvt_pk_bf16_f32 v54, v112, v113
	v_cvt_pk_bf16_f32 v55, v114, v115
	global_store_dwordx2 v[92:93], v[54:55], off
	v_pk_mul_f32 v[116:117], v[116:117], v[106:107]
	v_pk_mul_f32 v[118:119], v[118:119], v[106:107]
	v_pk_mul_f32 v[116:117], v[4:5], v[116:117]
	v_pk_mul_f32 v[118:119], v[6:7], v[118:119]
	v_pk_fma_f32 v[116:117], v[178:179], v[116:117], v[162:163]
	v_pk_fma_f32 v[118:119], v[180:181], v[118:119], v[164:165]
	v_cvt_pk_bf16_f32 v56, v116, v117
	v_cvt_pk_bf16_f32 v57, v118, v119
	global_store_dwordx2 v[92:93], v[56:57], off offset:512
	v_pk_mul_f32 v[120:121], v[120:121], v[106:107]
	v_pk_mul_f32 v[122:123], v[122:123], v[106:107]
	v_pk_mul_f32 v[120:121], v[8:9], v[120:121]
	v_pk_mul_f32 v[122:123], v[10:11], v[122:123]
	v_pk_fma_f32 v[120:121], v[182:183], v[120:121], v[166:167]
	v_pk_fma_f32 v[122:123], v[184:185], v[122:123], v[168:169]
	v_cvt_pk_bf16_f32 v54, v120, v121
	v_cvt_pk_bf16_f32 v55, v122, v123
	global_store_dwordx2 v[92:93], v[54:55], off offset:1024
	v_pk_mul_f32 v[124:125], v[124:125], v[106:107]
	v_pk_mul_f32 v[126:127], v[126:127], v[106:107]
	v_pk_mul_f32 v[124:125], v[12:13], v[124:125]
	v_pk_mul_f32 v[126:127], v[14:15], v[126:127]
	v_pk_fma_f32 v[124:125], v[186:187], v[124:125], v[170:171]
	v_pk_fma_f32 v[126:127], v[188:189], v[126:127], v[172:173]
	v_cvt_pk_bf16_f32 v56, v124, v125
	v_cvt_pk_bf16_f32 v57, v126, v127
	global_store_dwordx2 v[92:93], v[56:57], off offset:1536
	v_pk_mul_f32 v[52:53], v[128:129], v[128:129]
	v_pk_mul_f32 v[54:55], v[130:131], v[130:131]
	v_pk_fma_f32 v[52:53], v[132:133], v[132:133], v[52:53]
	v_pk_fma_f32 v[54:55], v[134:135], v[134:135], v[54:55]
	v_pk_fma_f32 v[52:53], v[136:137], v[136:137], v[52:53]
	v_pk_fma_f32 v[54:55], v[138:139], v[138:139], v[54:55]
	v_pk_fma_f32 v[52:53], v[140:141], v[140:141], v[52:53]
	v_pk_fma_f32 v[54:55], v[142:143], v[142:143], v[54:55]
	v_pk_add_f32 v[52:53], v[52:53], v[54:55]
	v_add_f32_e32 v97, v52, v53
	s_nop 1
	v_add_f32_dpp v97, v97, v97 quad_perm:[1,0,3,2] row_mask:0xf bank_mask:0xf
	s_nop 1
	v_add_f32_dpp v97, v97, v97 quad_perm:[2,3,0,1] row_mask:0xf bank_mask:0xf
	s_nop 1
	v_add_f32_dpp v97, v97, v97 row_ror:4 row_mask:0xf bank_mask:0xf
	s_nop 1
	v_add_f32_dpp v97, v97, v97 row_ror:8 row_mask:0xf bank_mask:0xf
	ds_bpermute_b32 v103, v108, v97
	v_add_u32_e32 v58, 0x3800, v96
	v_mov_b32_e32 v59, v147
	v_lshlrev_b64 v[92:93], 11, v[58:59]
	v_lshl_add_u64 v[92:93], v[100:101], 0, v[92:93]
	s_waitcnt lgkmcnt(0)
	v_add_f32_e32 v103, v97, v103
	ds_bpermute_b32 v106, v109, v103
	s_waitcnt lgkmcnt(0)
	v_add_f32_e32 v97, v103, v106
	v_fmamk_f32 v97, v97, 0x3a800000, v203
	v_mul_f32_e32 v103, 0x4f800000, v97
	v_cmp_gt_f32_e32 vcc, s26, v97
	s_nop 1
	v_cndmask_b32_e32 v97, v97, v103, vcc
	v_sqrt_f32_e32 v103, v97
	s_nop 0
	v_add_u32_e32 v106, -1, v103
	v_fma_f32 v111, -v106, v103, v97
	v_add_u32_e32 v107, 1, v103
	v_cmp_ge_f32_e64 s[42:43], 0, v111
	s_nop 1
	v_cndmask_b32_e64 v106, v103, v106, s[42:43]
	v_fma_f32 v103, -v107, v103, v97
	v_cmp_lt_f32_e64 s[42:43], 0, v103
	s_nop 1
	v_cndmask_b32_e64 v103, v106, v107, s[42:43]
	v_mul_f32_e32 v106, 0x37800000, v103
	v_cndmask_b32_e32 v103, v103, v106, vcc
	v_cmp_class_f32_e32 vcc, v97, v201
	s_nop 1
	v_cndmask_b32_e32 v97, v103, v97, vcc
	v_div_scale_f32 v103, s[30:31], v97, v97, 1.0
	v_rcp_f32_e32 v106, v103
	s_nop 0
	v_fma_f32 v107, -v103, v106, 1.0
	v_fmac_f32_e32 v106, v107, v106
	v_div_scale_f32 v107, vcc, 1.0, v97, 1.0
	v_mul_f32_e32 v111, v107, v106
	v_fma_f32 v45, -v103, v111, v107
	v_fmac_f32_e32 v111, v45, v106
	v_fma_f32 v103, -v103, v111, v107
	v_div_fmas_f32 v103, v103, v106, v111
	v_div_fixup_f32 v106, v103, v97, 1.0
	v_mov_b32_e32 v107, v106
	v_pk_mul_f32 v[128:129], v[128:129], v[106:107]
	v_pk_mul_f32 v[130:131], v[130:131], v[106:107]
	v_pk_mul_f32 v[128:129], v[0:1], v[128:129]
	v_pk_mul_f32 v[130:131], v[2:3], v[130:131]
	v_pk_fma_f32 v[128:129], v[174:175], v[128:129], v[158:159]
	v_pk_fma_f32 v[130:131], v[176:177], v[130:131], v[160:161]
	v_cvt_pk_bf16_f32 v54, v128, v129
	v_cvt_pk_bf16_f32 v55, v130, v131
	global_store_dwordx2 v[92:93], v[54:55], off
	v_pk_mul_f32 v[132:133], v[132:133], v[106:107]
	v_pk_mul_f32 v[134:135], v[134:135], v[106:107]
	v_pk_mul_f32 v[132:133], v[4:5], v[132:133]
	v_pk_mul_f32 v[134:135], v[6:7], v[134:135]
	v_pk_fma_f32 v[132:133], v[178:179], v[132:133], v[162:163]
	v_pk_fma_f32 v[134:135], v[180:181], v[134:135], v[164:165]
	v_cvt_pk_bf16_f32 v56, v132, v133
	v_cvt_pk_bf16_f32 v57, v134, v135
	global_store_dwordx2 v[92:93], v[56:57], off offset:512
	v_pk_mul_f32 v[136:137], v[136:137], v[106:107]
	v_pk_mul_f32 v[138:139], v[138:139], v[106:107]
	v_pk_mul_f32 v[136:137], v[8:9], v[136:137]
	v_pk_mul_f32 v[138:139], v[10:11], v[138:139]
	v_pk_fma_f32 v[136:137], v[182:183], v[136:137], v[166:167]
	v_pk_fma_f32 v[138:139], v[184:185], v[138:139], v[168:169]
	v_cvt_pk_bf16_f32 v54, v136, v137
	v_cvt_pk_bf16_f32 v55, v138, v139
	global_store_dwordx2 v[92:93], v[54:55], off offset:1024
	v_pk_mul_f32 v[140:141], v[140:141], v[106:107]
	v_pk_mul_f32 v[142:143], v[142:143], v[106:107]
	v_pk_mul_f32 v[140:141], v[12:13], v[140:141]
	v_pk_mul_f32 v[142:143], v[14:15], v[142:143]
	v_pk_fma_f32 v[140:141], v[186:187], v[140:141], v[170:171]
	v_pk_fma_f32 v[142:143], v[188:189], v[142:143], v[172:173]
	v_cvt_pk_bf16_f32 v56, v140, v141
	v_cvt_pk_bf16_f32 v57, v142, v143
	global_store_dwordx2 v[92:93], v[56:57], off offset:1536
	v_add_u32_e32 v96, 0x4000, v96
	v_cmp_gt_i32_e32 vcc, s37, v96
	s_cbranch_vccz .Lnp_fast_done
; DI unsigned pk2(float lo, float hi) { const f32x2 v = {lo, hi}; const hbf16x2 b = __builtin_convertvector(v, hbf16x2); return __builtin_bit_cast(unsigned, b); }
; #define NP_LOAD(dst_, r_) do { const float* s_ = NP_SRC(r_); _Pragma("unroll") for (int j = 0; j < 4; ++j) dst_[j] = *(const f32x4*)(s_ + 4 * lane + 256 * j); } while (0)
; DI void norm_phase(const Ctx& a, int layer, int sub, bool first, const float* P, int nsl, int nrows) {
;     ...
;     for (int row = rbeg; row < rend; row += NGW) {
; #pragma unroll
;         for (int j = 0; j < 4; ++j) { v[j] = n1[j]; n1[j] = n2[j]; }
;         if (row + 2 * NGW < rend) NP_LOAD(n2, row + 2 * NGW);
;         const int mr = row < ML ? (row >> 12) : 4;
;         if (mr != mr_cur) { mr_cur = mr;
; #pragma unroll
;             for (int j = 0; j < 4; ++j) { sh[j] = *(const f32x4*)(modl + (size_t)mr * MODW + 4 * lane + 256 * j); sc[j] = *(const f32x4*)(modl + (size_t)mr * MODW + 1024 + 4 * lane + 256 * j) + 1.f; } }
;         const bool fold = !first && row >= ML;
;         float ss = 0.f;
;         if (fold) {
;             for (int sl0 = 0; sl0 < nsl; sl0 += 4) {
;                 f32x4 t[4][4]; float wq[4];
; #pragma unroll
;                 for (int u = 0; u < 4; ++u) { const int sl = sl0 + u < nsl ? sl0 + u : nsl - 1; wq[u] = sl0 + u < nsl ? 1.f : 0.f;
; #pragma unroll
;                     for (int j = 0; j < 4; ++j) t[u][j] = *(const f32x4*)(P + ((size_t)sl * MC + (row - ML)) * D + 4 * lane + 256 * j); }
; #pragma unroll
;                 for (int u = 0; u < 4; ++u)
; #pragma unroll
;                     for (int j = 0; j < 4; ++j) v[j] = v[j] + t[u][j] * wq[u];
;             }
;         }
; #pragma unroll
;         for (int j = 0; j < 4; ++j) ss += (v[j][0] * v[j][0] + v[j][1] * v[j][1]) + (v[j][2] * v[j][2] + v[j][3] * v[j][3]);
;         const float rstd = 1.f / sqrtf(wave_sum(ss, lane) * (1.f / 1024.f) + 1e-6f);
; #pragma unroll
;         for (int j = 0; j < 4; ++j) {
;             const int c = 4 * lane + 256 * j;
;             if ((first && row >= ML) || fold) *(f32x4*)(H + (size_t)row * 1024 + c) = v[j];
;             f32x4 y = v[j] * rstd * gg[j]; y = y * sc[j] + sh[j];
;             u32x2 w; w.x = pk2(y[0], y[1]); w.y = pk2(y[2], y[3]);
;             *(u32x2*)(XN + (size_t)row * 1024 + c) = w;
;         }
;     }
	v_mov_b32_e32 v97, v147
	v_lshlrev_b64 v[94:95], 12, v[96:97]
	v_lshl_add_u64 v[94:95], s[34:35], 0, v[94:95]
	v_lshl_add_u64 v[94:95], v[94:95], 0, v[146:147]
	global_load_dwordx4 v[28:31], v[94:95], off
	global_load_dwordx4 v[24:27], v[94:95], off offset:1024
	global_load_dwordx4 v[20:23], v[94:95], off offset:2048
	global_load_dwordx4 v[16:19], v[94:95], off offset:3072
	v_mov_b32_e32 v110, -1
	s_branch .LBB0_503
.Lnp_fast_done:
	s_branch .LBB0_526
.LBB0_502:
	s_or_b64 exec, exec, s[30:31]
	v_mov_b32_e32 v20, v106
	v_mov_b32_e32 v21, v106
	v_pk_mul_f32 v[18:19], v[18:19], v[20:21]
	v_pk_mul_f32 v[16:17], v[16:17], v[106:107]
	v_pk_mul_f32 v[18:19], v[14:15], v[18:19]
	v_pk_mul_f32 v[16:17], v[12:13], v[16:17]
	s_waitcnt vmcnt(3)
	v_pk_fma_f32 v[18:19], v[94:95], v[18:19], v[78:79]
	v_pk_fma_f32 v[16:17], v[92:93], v[16:17], v[76:77]
	v_subrev_u32_e32 v96, s25, v102
	v_cvt_pk_bf16_f32 v16, v16, v17
	v_cvt_pk_bf16_f32 v17, v18, v19
	global_store_dwordx2 v[28:29], v[16:17], off offset:1536
	v_cmp_le_i32_e32 vcc, s37, v96
	v_mov_b64_e32 v[28:29], v[64:65]
	v_mov_b64_e32 v[24:25], v[56:57]
	v_mov_b64_e32 v[20:21], v[52:53]
	v_mov_b64_e32 v[16:17], v[44:45]
	s_or_b64 s[44:45], vcc, s[44:45]
	v_mov_b64_e32 v[30:31], v[66:67]
	v_mov_b64_e32 v[26:27], v[58:59]
	v_mov_b64_e32 v[22:23], v[54:55]
	v_mov_b64_e32 v[18:19], v[46:47]
	s_andn2_b64 exec, exec, s[44:45]
	s_cbranch_execz .LBB0_526
